# attention epilogue: row-per-lane O stores widened to 16 bytes with v_permlane32_swap pairs (4 stores per lane instead of 8)
# baseline (speedup 1.0000x reference)
.Lat_qb:
	s_lshl_b32 s9, s2, 2
	s_lshr_b32 s10, s3, 1
	s_add_u32 s10, s10, s9
	s_add_u32 s11, s9, 3
	s_add_u32 s9, s9, 4
	s_lshl_b32 s18, s2, 8
	s_lshl_b32 s19, s3, 5
	s_add_u32 s18, s18, s19
	v_and_b32_e32 v235, 31, v186
	v_bfe_u32 v237, v186, 5, 1
	v_add_u32_e32 v235, s18, v235
	v_lshlrev_b32_e32 v219, 10, v235
	v_mul_u32_u24_e32 v236, 0x2cb0, v235
	v_lshl_add_u32 v220, v237, 4, v236
	v_lshl_add_u32 v197, v237, 4, v236
	global_load_dwordx4 v[102:105], v220, s[4:5] offset:0
	global_load_dwordx4 v[106:109], v220, s[4:5] offset:32
	global_load_dwordx4 v[110:113], v220, s[4:5] offset:64
	global_load_dwordx4 v[114:117], v220, s[4:5] offset:96
	s_mov_b64 s[12:13], s[4:5]
	s_add_i32 m0, s58, 0x0
	s_nop 0
	global_load_lds_dwordx4 v221, s[12:13]
	s_add_i32 m0, s58, 0x8000
	s_nop 0
	global_load_lds_dwordx4 v222, s[12:13]
	s_add_u32 s12, s12, 0xb2c00
	s_addc_u32 s13, s13, 0
	s_add_i32 m0, s58, 0x2000
	s_nop 0
	global_load_lds_dwordx4 v221, s[12:13]
	s_add_u32 s12, s12, 0xb2c00
	s_addc_u32 s13, s13, 0
	s_add_i32 m0, s58, 0x4000
	s_nop 0
	global_load_lds_dwordx4 v221, s[12:13]
	s_add_u32 s12, s12, 0xb2c00
	s_addc_u32 s13, s13, 0
	global_load_dwordx4 v[198:201], v219, s[6:7]
	s_add_i32 m0, s58, 0x6000
	s_nop 0
	global_load_lds_dwordx4 v221, s[12:13]
	s_add_u32 s14, s4, 0xb2c00
	s_addc_u32 s15, s5, 0
	s_add_i32 m0, s58, 0xa000
	s_nop 0
	global_load_lds_dwordx4 v222, s[14:15]
	v_mov_b32_e32 v230, 0xff800000
	v_mov_b32_e32 v231, 0
	v_mov_b32_e32 v0, 0
	v_mov_b32_e32 v1, 0
	v_mov_b32_e32 v2, 0
	v_mov_b32_e32 v3, 0
	v_mov_b32_e32 v4, 0
	v_mov_b32_e32 v5, 0
	v_mov_b32_e32 v6, 0
	v_mov_b32_e32 v7, 0
	v_mov_b32_e32 v8, 0
	v_mov_b32_e32 v9, 0
	v_mov_b32_e32 v10, 0
	v_mov_b32_e32 v11, 0
	v_mov_b32_e32 v12, 0
	v_mov_b32_e32 v13, 0
	v_mov_b32_e32 v14, 0
	v_mov_b32_e32 v15, 0
	v_mov_b32_e32 v16, 0
	v_mov_b32_e32 v17, 0
	v_mov_b32_e32 v18, 0
	v_mov_b32_e32 v19, 0
	v_mov_b32_e32 v20, 0
	v_mov_b32_e32 v21, 0
	v_mov_b32_e32 v22, 0
	v_mov_b32_e32 v23, 0
	v_mov_b32_e32 v24, 0
	v_mov_b32_e32 v25, 0
	v_mov_b32_e32 v26, 0
	v_mov_b32_e32 v27, 0
	v_mov_b32_e32 v28, 0
	v_mov_b32_e32 v29, 0
	v_mov_b32_e32 v30, 0
	v_mov_b32_e32 v31, 0
	s_waitcnt vmcnt(2)
	s_barrier
	ds_read_b128 v[118:121], v223 offset:0
	ds_read_b128 v[122:125], v223 offset:4096
	ds_read_b128 v[126:129], v224 offset:0
	ds_read_b128 v[130:133], v224 offset:4096
	ds_read_b128 v[134:137], v225 offset:0
	ds_read_b128 v[138:141], v225 offset:4096
	ds_read_b128 v[142:145], v226 offset:0
	ds_read_b128 v[146:149], v226 offset:4096
	s_waitcnt lgkmcnt(0)
	s_barrier
	v_mfma_f32_32x32x16_bf16 v[34:49], v[118:121], v[102:105], 0
	v_mfma_f32_32x32x16_bf16 v[50:65], v[122:125], v[102:105], 0
	v_mfma_f32_32x32x16_bf16 v[34:49], v[126:129], v[106:109], v[34:49]
	v_mfma_f32_32x32x16_bf16 v[50:65], v[130:133], v[106:109], v[50:65]
	v_mfma_f32_32x32x16_bf16 v[34:49], v[134:137], v[110:113], v[34:49]
	v_mfma_f32_32x32x16_bf16 v[50:65], v[138:141], v[110:113], v[50:65]
	v_mfma_f32_32x32x16_bf16 v[34:49], v[142:145], v[114:117], v[34:49]
	v_mfma_f32_32x32x16_bf16 v[50:65], v[146:149], v[114:117], v[50:65]
	ds_read_b128 v[118:121], v223 offset:8192
	ds_read_b128 v[122:125], v223 offset:12288
	ds_read_b128 v[126:129], v224 offset:8192
	ds_read_b128 v[130:133], v224 offset:12288
	ds_read_b128 v[134:137], v225 offset:8192
	ds_read_b128 v[138:141], v225 offset:12288
	ds_read_b128 v[142:145], v226 offset:8192
	ds_read_b128 v[146:149], v226 offset:12288
	s_waitcnt lgkmcnt(14)
	s_mov_b32 s8, 0
	s_nop 7
	v_lshrrev_b32_e32 v249, v229, v198
	v_lshrrev_b32_e32 v250, v229, v199
	v_bfe_i32 v235, v249, 0, 1
	v_bfe_i32 v236, v250, 0, 1
	v_bfe_i32 v237, v249, 1, 1
	v_bfe_i32 v238, v250, 1, 1
	v_bfe_i32 v239, v249, 2, 1
	v_bfe_i32 v240, v250, 2, 1
	v_bfe_i32 v241, v249, 3, 1
	v_bfe_i32 v242, v250, 3, 1
	v_bitop3_b32 v34, v34, s33, v235 bitop3:0xe4
	v_bitop3_b32 v50, v50, s33, v236 bitop3:0xe4
	v_bitop3_b32 v35, v35, s33, v237 bitop3:0xe4
	v_bitop3_b32 v51, v51, s33, v238 bitop3:0xe4
	v_bitop3_b32 v36, v36, s33, v239 bitop3:0xe4
	v_bitop3_b32 v52, v52, s33, v240 bitop3:0xe4
	v_bitop3_b32 v37, v37, s33, v241 bitop3:0xe4
	v_bitop3_b32 v53, v53, s33, v242 bitop3:0xe4
	v_max3_f32 v247, v34, s33, v50
	v_max3_f32 v248, v35, s33, v51
	v_max3_f32 v247, v247, v36, v52
	v_max3_f32 v248, v248, v37, v53
	v_bfe_i32 v235, v249, 8, 1
	v_bfe_i32 v236, v250, 8, 1
	v_bfe_i32 v237, v249, 9, 1
	v_bfe_i32 v238, v250, 9, 1
	v_bfe_i32 v239, v249, 10, 1
	v_bfe_i32 v240, v250, 10, 1
	v_bfe_i32 v241, v249, 11, 1
	v_bfe_i32 v242, v250, 11, 1
	v_bitop3_b32 v38, v38, s33, v235 bitop3:0xe4
	v_bitop3_b32 v54, v54, s33, v236 bitop3:0xe4
	v_bitop3_b32 v39, v39, s33, v237 bitop3:0xe4
	v_bitop3_b32 v55, v55, s33, v238 bitop3:0xe4
	v_bitop3_b32 v40, v40, s33, v239 bitop3:0xe4
	v_bitop3_b32 v56, v56, s33, v240 bitop3:0xe4
	v_bitop3_b32 v41, v41, s33, v241 bitop3:0xe4
	v_bitop3_b32 v57, v57, s33, v242 bitop3:0xe4
	v_max3_f32 v247, v247, v38, v54
	v_max3_f32 v248, v248, v39, v55
	v_max3_f32 v247, v247, v40, v56
	v_max3_f32 v248, v248, v41, v57
	v_bfe_i32 v235, v249, 16, 1
	v_bfe_i32 v236, v250, 16, 1
	v_bfe_i32 v237, v249, 17, 1
	v_bfe_i32 v238, v250, 17, 1
	v_bfe_i32 v239, v249, 18, 1
	v_bfe_i32 v240, v250, 18, 1
	v_bfe_i32 v241, v249, 19, 1
	v_bfe_i32 v242, v250, 19, 1
	v_bitop3_b32 v42, v42, s33, v235 bitop3:0xe4
	v_bitop3_b32 v58, v58, s33, v236 bitop3:0xe4
	v_bitop3_b32 v43, v43, s33, v237 bitop3:0xe4
	v_bitop3_b32 v59, v59, s33, v238 bitop3:0xe4
	v_bitop3_b32 v44, v44, s33, v239 bitop3:0xe4
	v_bitop3_b32 v60, v60, s33, v240 bitop3:0xe4
	v_bitop3_b32 v45, v45, s33, v241 bitop3:0xe4
	v_bitop3_b32 v61, v61, s33, v242 bitop3:0xe4
	v_max3_f32 v247, v247, v42, v58
	v_max3_f32 v248, v248, v43, v59
	v_max3_f32 v247, v247, v44, v60
	v_max3_f32 v248, v248, v45, v61
	v_bfe_i32 v235, v249, 24, 1
	v_bfe_i32 v236, v250, 24, 1
	v_bfe_i32 v237, v249, 25, 1
	v_bfe_i32 v238, v250, 25, 1
	v_bfe_i32 v239, v249, 26, 1
	v_bfe_i32 v240, v250, 26, 1
	v_bfe_i32 v241, v249, 27, 1
	v_bfe_i32 v242, v250, 27, 1
	v_bitop3_b32 v46, v46, s33, v235 bitop3:0xe4
	v_bitop3_b32 v62, v62, s33, v236 bitop3:0xe4
	v_bitop3_b32 v47, v47, s33, v237 bitop3:0xe4
	v_bitop3_b32 v63, v63, s33, v238 bitop3:0xe4
	v_bitop3_b32 v48, v48, s33, v239 bitop3:0xe4
	v_bitop3_b32 v64, v64, s33, v240 bitop3:0xe4
	v_bitop3_b32 v49, v49, s33, v241 bitop3:0xe4
	v_bitop3_b32 v65, v65, s33, v242 bitop3:0xe4
	v_max3_f32 v247, v247, v46, v62
	v_max3_f32 v248, v248, v47, v63
	v_max3_f32 v247, v247, v48, v64
	v_max3_f32 v248, v248, v49, v65
	v_max_f32_e32 v247, v247, v248
	v_mov_b32_e32 v248, v247
	s_nop 1
	v_permlane32_swap_b32_e32 v247, v248
	v_max3_f32 v247, v230, v247, v248
	v_cmp_neq_f32_e32 vcc, s33, v247
	s_nop 1
	v_cndmask_b32_e32 v248, 0, v247, vcc
	v_sub_f32_e32 v33, v230, v248
	v_mul_f32_e32 v33, 0x3e38aa3b, v33
	v_exp_f32_e32 v232, v33
	v_mul_f32_e32 v234, 0xbe38aa3b, v248
	v_mov_b32_e32 v230, v247

.Lat_epilogue:
	v_mov_b32_e32 v248, v231
	v_mov_b32_e32 v247, v231
	s_nop 1
	v_permlane32_swap_b32_e32 v247, v248
	v_add_f32_e32 v247, v247, v248
	v_div_scale_f32 v235, s[18:19], v247, v247, 1.0
	v_rcp_f32_e32 v236, v235
	v_div_scale_f32 v237, vcc, 1.0, v247, 1.0
	v_fma_f32 v238, -v235, v236, 1.0
	v_fmac_f32_e32 v236, v238, v236
	v_mul_f32_e32 v238, v237, v236
	v_fma_f32 v239, -v235, v238, v237
	v_fmac_f32_e32 v238, v239, v236
	v_fma_f32 v235, -v235, v238, v237
	v_div_fmas_f32 v235, v235, v236, v238
	v_div_fixup_f32 v33, v235, v247, 1.0
	v_mul_f32_e32 v235, v0, v33
	v_mul_f32_e32 v236, v1, v33
	v_mul_f32_e32 v237, v2, v33
	v_mul_f32_e32 v238, v3, v33
	v_mul_f32_e32 v239, v4, v33
	v_mul_f32_e32 v240, v5, v33
	v_mul_f32_e32 v241, v6, v33
	v_mul_f32_e32 v242, v7, v33
	v_cvt_pk_bf16_f32 v244, v235, v236
	v_cvt_pk_bf16_f32 v245, v237, v238
	v_cvt_pk_bf16_f32 v246, v239, v240
	v_cvt_pk_bf16_f32 v247, v241, v242
	s_nop 1
	v_permlane32_swap_b32_e32 v244, v246
	v_permlane32_swap_b32_e32 v245, v247
	global_store_dwordx4 v197, v[244:247], s[4:5] offset:0
	v_mul_f32_e32 v235, v8, v33
	v_mul_f32_e32 v236, v9, v33
	v_mul_f32_e32 v237, v10, v33
	v_mul_f32_e32 v238, v11, v33
	v_mul_f32_e32 v239, v12, v33
	v_mul_f32_e32 v240, v13, v33
	v_mul_f32_e32 v241, v14, v33
	v_mul_f32_e32 v242, v15, v33
	v_cvt_pk_bf16_f32 v244, v235, v236
	v_cvt_pk_bf16_f32 v245, v237, v238
	v_cvt_pk_bf16_f32 v246, v239, v240
	v_cvt_pk_bf16_f32 v247, v241, v242
	s_nop 1
	v_permlane32_swap_b32_e32 v244, v246
	v_permlane32_swap_b32_e32 v245, v247
	global_store_dwordx4 v197, v[244:247], s[4:5] offset:32
	v_mul_f32_e32 v235, v16, v33
	v_mul_f32_e32 v236, v17, v33
	v_mul_f32_e32 v237, v18, v33
	v_mul_f32_e32 v238, v19, v33
	v_mul_f32_e32 v239, v20, v33
	v_mul_f32_e32 v240, v21, v33
	v_mul_f32_e32 v241, v22, v33
	v_mul_f32_e32 v242, v23, v33
	v_cvt_pk_bf16_f32 v244, v235, v236
	v_cvt_pk_bf16_f32 v245, v237, v238
	v_cvt_pk_bf16_f32 v246, v239, v240
	v_cvt_pk_bf16_f32 v247, v241, v242
	s_nop 1
	v_permlane32_swap_b32_e32 v244, v246
	v_permlane32_swap_b32_e32 v245, v247
	global_store_dwordx4 v197, v[244:247], s[4:5] offset:64
	v_mul_f32_e32 v235, v24, v33
	v_mul_f32_e32 v236, v25, v33
	v_mul_f32_e32 v237, v26, v33
	v_mul_f32_e32 v238, v27, v33
	v_mul_f32_e32 v239, v28, v33
	v_mul_f32_e32 v240, v29, v33
	v_mul_f32_e32 v241, v30, v33
	v_mul_f32_e32 v242, v31, v33
	v_cvt_pk_bf16_f32 v244, v235, v236
	v_cvt_pk_bf16_f32 v245, v237, v238
	v_cvt_pk_bf16_f32 v246, v239, v240
	v_cvt_pk_bf16_f32 v247, v241, v242
	s_nop 1
	v_permlane32_swap_b32_e32 v244, v246
	v_permlane32_swap_b32_e32 v245, v247
	global_store_dwordx4 v197, v[244:247], s[4:5] offset:96
	s_add_u32 s1, s1, 1
	s_cmp_lt_u32 s1, 2
	s_cbranch_scc1 .Lat_unit
	s_add_u32 s0, s0, s84
	s_branch .Lat_item
